# hand-written XCD grid barrier at the six in-loop sites: XCD leaders post the top-level arrival and poll the top counter (no returned-value round trip, no separate generation word)
# speedup vs baseline: 1.0170x; 1.0063x over previous
.LBB0_640:
	s_mov_b64 s[0:1], s[88:89]
	s_getreg_b32 s8, hwreg(HW_REG_XCC_ID, 0, 4)
	s_waitcnt vmcnt(0)
	s_waitcnt lgkmcnt(0)
	s_barrier
	s_mov_b64 s[10:11], exec
	v_readlane_b32 s12, v254, 5
	v_readlane_b32 s13, v254, 6
	s_and_b64 s[12:13], s[10:11], s[12:13]
	s_mov_b64 exec, s[12:13]
	s_cbranch_execz .LBB0_450
	buffer_inv sc1
	s_load_dwordx2 s[22:23], s[0:1], 0x170
	v_readlane_b32 s24, v254, 45
	v_readlane_b32 s25, v254, 46
	s_and_b32 s8, s8, 15
	v_mov_b32_e32 v0, s24
	v_mov_b32_e32 v1, s25
	ds_read_b32 v2, v0
	ds_read_b32 v3, v1
	s_lshl_b32 s9, s8, 8
	v_mov_b32_e32 v4, 0x1400
	v_mov_b32_e32 v5, 1
	s_waitcnt lgkmcnt(0)
	s_add_u32 s24, s22, s9
	s_addc_u32 s25, s23, 0
	global_atomic_add v6, v4, v5, s[24:25] sc0
	v_cvt_f32_u32_e32 v7, v2
	v_rcp_f32_e32 v7, v7
	s_waitcnt vmcnt(0)
	v_cvt_f32_u32_e32 v8, v6
	v_add_f32_e32 v8, 0.5, v8
	v_mul_f32_e32 v8, v8, v7
	v_cvt_u32_f32_e32 v8, v8
	v_mul_lo_u32 v9, v8, v2
	v_sub_u32_e32 v9, v6, v9
	v_add_u32_e32 v9, 1, v9
	v_cmp_eq_u32_e32 vcc, v9, v2
	v_readfirstlane_b32 s26, v8
	s_cbranch_vccz .Lhb0_follow
	buffer_wbl2 sc1
	s_waitcnt vmcnt(0)
	v_mov_b32_e32 v4, 0x3400
	global_atomic_add v4, v5, s[22:23]
	v_readfirstlane_b32 s27, v3
	s_add_u32 s34, s26, 1
	s_mul_i32 s27, s34, s27
	s_mov_b32 s35, 0
.Lhb0_lspin:
	global_load_dword v10, v4, s[22:23] sc1
	s_waitcnt vmcnt(0)
	v_readfirstlane_b32 s36, v10
	s_sub_u32 s36, s36, s27
	s_cmp_ge_i32 s36, 0
	s_cbranch_scc1 .Lhb0_ldone
	s_sleep 1
	s_add_u32 s35, s35, 1
	s_cmp_lt_u32 s35, 0x400000
	s_cbranch_scc1 .Lhb0_lspin
.Lhb0_ldone:
	v_mov_b32_e32 v4, 0x2400
	global_atomic_add v4, v5, s[24:25]
	s_waitcnt vmcnt(0)
	s_branch .LBB0_450
.Lhb0_follow:
	v_mov_b32_e32 v4, 0x2400
	s_mov_b32 s35, 0
.Lhb0_fspin:
	global_load_dword v10, v4, s[24:25] sc1
	s_waitcnt vmcnt(0)
	v_readfirstlane_b32 s36, v10
	s_cmp_lg_u32 s36, s26
	s_cbranch_scc1 .LBB0_450
	s_sleep 1
	s_add_u32 s35, s35, 1
	s_cmp_lt_u32 s35, 0x400000
	s_cbranch_scc1 .Lhb0_fspin
	s_branch .LBB0_450
	buffer_inv sc1
	s_load_dwordx2 s[12:13], s[0:1], 0x170
	v_readlane_b32 s0, v254, 45
	s_waitcnt expcnt(0) lgkmcnt(0)
	s_and_b32 s36, s8, 15
	v_mov_b32_e32 v0, s0
	ds_read_b32 v2, v0
	v_readlane_b32 s0, v254, 46
	s_waitcnt lgkmcnt(0)
	v_cmp_ne_u32_e32 vcc, 0, v2
	v_mov_b32_e32 v0, s0
	ds_read_b32 v0, v0
	s_cbranch_vccnz .LBB0_656
	s_add_u32 s14, s12, 0x1000
	s_addc_u32 s15, s13, 0
	s_add_u32 s20, s12, 0x1100
	s_addc_u32 s21, s13, 0
	s_add_u32 s22, s12, 0x1200
	s_addc_u32 s23, s13, 0
	s_add_u32 s24, s12, 0x1300
	s_addc_u32 s25, s13, 0
	s_mov_b32 s8, 1
	s_branch .LBB0_644

.LBB0_949:
	s_mov_b64 s[0:1], s[88:89]
	s_getreg_b32 s8, hwreg(HW_REG_XCC_ID, 0, 4)
	s_waitcnt vmcnt(0)
	s_barrier
	s_mov_b64 s[2:3], exec
	v_readlane_b32 s10, v254, 5
	v_readlane_b32 s11, v254, 6
	s_and_b64 s[10:11], s[2:3], s[10:11]
	s_mov_b64 exec, s[10:11]
	s_cbranch_execz .LBB0_694
	buffer_inv sc1
	s_load_dwordx2 s[22:23], s[0:1], 0x170
	v_readlane_b32 s24, v254, 45
	v_readlane_b32 s25, v254, 46
	s_and_b32 s8, s8, 15
	v_mov_b32_e32 v0, s24
	v_mov_b32_e32 v1, s25
	ds_read_b32 v2, v0
	ds_read_b32 v3, v1
	s_lshl_b32 s9, s8, 8
	v_mov_b32_e32 v4, 0x1400
	v_mov_b32_e32 v5, 1
	s_waitcnt lgkmcnt(0)
	s_add_u32 s24, s22, s9
	s_addc_u32 s25, s23, 0
	global_atomic_add v6, v4, v5, s[24:25] sc0
	v_cvt_f32_u32_e32 v7, v2
	v_rcp_f32_e32 v7, v7
	s_waitcnt vmcnt(0)
	v_cvt_f32_u32_e32 v8, v6
	v_add_f32_e32 v8, 0.5, v8
	v_mul_f32_e32 v8, v8, v7
	v_cvt_u32_f32_e32 v8, v8
	v_mul_lo_u32 v9, v8, v2
	v_sub_u32_e32 v9, v6, v9
	v_add_u32_e32 v9, 1, v9
	v_cmp_eq_u32_e32 vcc, v9, v2
	v_readfirstlane_b32 s26, v8
	s_cbranch_vccz .Lhb1_follow
	buffer_wbl2 sc1
	s_waitcnt vmcnt(0)
	v_mov_b32_e32 v4, 0x3400
	global_atomic_add v4, v5, s[22:23]
	v_readfirstlane_b32 s27, v3
	s_add_u32 s34, s26, 1
	s_mul_i32 s27, s34, s27
	s_mov_b32 s35, 0

.Lhb1_fspin:
	global_load_dword v10, v4, s[24:25] sc1
	s_waitcnt vmcnt(0)
	v_readfirstlane_b32 s36, v10
	s_cmp_lg_u32 s36, s26
	s_cbranch_scc1 .LBB0_694
	s_sleep 1
	s_add_u32 s35, s35, 1
	s_cmp_lt_u32 s35, 0x400000
	s_cbranch_scc1 .Lhb1_fspin
	s_branch .LBB0_694
	buffer_inv sc1
	s_load_dwordx2 s[10:11], s[0:1], 0x170
	v_readlane_b32 s0, v254, 45
	s_waitcnt expcnt(0) lgkmcnt(0)
	s_and_b32 s16, s8, 15
	v_mov_b32_e32 v0, s0
	ds_read_b32 v2, v0
	v_readlane_b32 s0, v254, 46
	s_waitcnt lgkmcnt(0)
	v_cmp_ne_u32_e32 vcc, 0, v2
	v_mov_b32_e32 v0, s0
	ds_read_b32 v0, v0
	s_cbranch_vccnz .LBB0_965
	s_add_u32 s12, s10, 0x1000
	s_addc_u32 s13, s11, 0
	s_add_u32 s14, s10, 0x1100
	s_addc_u32 s15, s11, 0
	s_add_u32 s20, s10, 0x1200
	s_addc_u32 s21, s11, 0
	s_add_u32 s22, s10, 0x1300
	s_addc_u32 s23, s11, 0
	s_mov_b32 s8, 1
	s_branch .LBB0_953

.LBB0_1033:
	s_mov_b64 s[0:1], s[88:89]
	s_getreg_b32 s8, hwreg(HW_REG_XCC_ID, 0, 4)
	s_waitcnt vmcnt(0)
	s_waitcnt vmcnt(63) expcnt(7) lgkmcnt(15)
	s_barrier
	s_mov_b64 s[10:11], exec
	v_readlane_b32 s12, v254, 5
	v_readlane_b32 s13, v254, 6
	s_and_b64 s[12:13], s[10:11], s[12:13]
	s_mov_b64 exec, s[12:13]
	s_cbranch_execz .LBB0_1003
	buffer_inv sc1
	s_load_dwordx2 s[22:23], s[0:1], 0x170
	v_readlane_b32 s24, v254, 45
	v_readlane_b32 s25, v254, 46
	s_and_b32 s8, s8, 15
	v_mov_b32_e32 v0, s24
	v_mov_b32_e32 v1, s25
	ds_read_b32 v2, v0
	ds_read_b32 v3, v1
	s_lshl_b32 s9, s8, 8
	v_mov_b32_e32 v4, 0x1400
	v_mov_b32_e32 v5, 1
	s_waitcnt lgkmcnt(0)
	s_add_u32 s24, s22, s9
	s_addc_u32 s25, s23, 0
	global_atomic_add v6, v4, v5, s[24:25] sc0
	v_cvt_f32_u32_e32 v7, v2
	v_rcp_f32_e32 v7, v7
	s_waitcnt vmcnt(0)
	v_cvt_f32_u32_e32 v8, v6
	v_add_f32_e32 v8, 0.5, v8
	v_mul_f32_e32 v8, v8, v7
	v_cvt_u32_f32_e32 v8, v8
	v_mul_lo_u32 v9, v8, v2
	v_sub_u32_e32 v9, v6, v9
	v_add_u32_e32 v9, 1, v9
	v_cmp_eq_u32_e32 vcc, v9, v2
	v_readfirstlane_b32 s26, v8
	s_cbranch_vccz .Lhb2_follow
	buffer_wbl2 sc1
	s_waitcnt vmcnt(0)
	v_mov_b32_e32 v4, 0x3400
	global_atomic_add v4, v5, s[22:23]
	v_readfirstlane_b32 s27, v3
	s_add_u32 s34, s26, 1
	s_mul_i32 s27, s34, s27
	s_mov_b32 s35, 0

.Lhb2_fspin:
	global_load_dword v10, v4, s[24:25] sc1
	s_waitcnt vmcnt(0)
	v_readfirstlane_b32 s36, v10
	s_cmp_lg_u32 s36, s26
	s_cbranch_scc1 .LBB0_1003
	s_sleep 1
	s_add_u32 s35, s35, 1
	s_cmp_lt_u32 s35, 0x400000
	s_cbranch_scc1 .Lhb2_fspin
	s_branch .LBB0_1003
	buffer_inv sc1
	s_load_dwordx2 s[12:13], s[0:1], 0x170
	v_readlane_b32 s0, v254, 45
	s_waitcnt expcnt(0) lgkmcnt(0)
	s_and_b32 s16, s8, 15
	v_mov_b32_e32 v0, s0
	ds_read_b32 v2, v0
	v_readlane_b32 s0, v254, 46
	s_waitcnt lgkmcnt(0)
	v_cmp_ne_u32_e32 vcc, 0, v2
	v_mov_b32_e32 v0, s0
	ds_read_b32 v0, v0
	s_cbranch_vccnz .LBB0_1049
	s_add_u32 s14, s12, 0x1000
	s_addc_u32 s15, s13, 0
	s_add_u32 s20, s12, 0x1100
	s_addc_u32 s21, s13, 0
	s_add_u32 s22, s12, 0x1200
	s_addc_u32 s23, s13, 0
	s_add_u32 s24, s12, 0x1300
	s_addc_u32 s25, s13, 0
	s_mov_b32 s8, 1
	s_branch .LBB0_1037

.LBB0_1107:
	s_mov_b64 s[0:1], s[88:89]
	s_getreg_b32 s8, hwreg(HW_REG_XCC_ID, 0, 4)
	s_waitcnt vmcnt(0)
	s_waitcnt lgkmcnt(0)
	s_barrier
	s_mov_b64 s[2:3], exec
	v_readlane_b32 s10, v254, 5
	v_readlane_b32 s11, v254, 6
	s_and_b64 s[10:11], s[2:3], s[10:11]
	s_mov_b64 exec, s[10:11]
	s_cbranch_execz .LBB0_1159
	buffer_inv sc1
	s_load_dwordx2 s[22:23], s[0:1], 0x170
	v_readlane_b32 s24, v254, 45
	v_readlane_b32 s25, v254, 46
	s_and_b32 s8, s8, 15
	v_mov_b32_e32 v0, s24
	v_mov_b32_e32 v1, s25
	ds_read_b32 v2, v0
	ds_read_b32 v3, v1
	s_lshl_b32 s9, s8, 8
	v_mov_b32_e32 v4, 0x1400
	v_mov_b32_e32 v5, 1
	s_waitcnt lgkmcnt(0)
	s_add_u32 s24, s22, s9
	s_addc_u32 s25, s23, 0
	global_atomic_add v6, v4, v5, s[24:25] sc0
	v_cvt_f32_u32_e32 v7, v2
	v_rcp_f32_e32 v7, v7
	s_waitcnt vmcnt(0)
	v_cvt_f32_u32_e32 v8, v6
	v_add_f32_e32 v8, 0.5, v8
	v_mul_f32_e32 v8, v8, v7
	v_cvt_u32_f32_e32 v8, v8
	v_mul_lo_u32 v9, v8, v2
	v_sub_u32_e32 v9, v6, v9
	v_add_u32_e32 v9, 1, v9
	v_cmp_eq_u32_e32 vcc, v9, v2
	v_readfirstlane_b32 s26, v8
	s_cbranch_vccz .Lhb3_follow
	buffer_wbl2 sc1
	s_waitcnt vmcnt(0)
	v_mov_b32_e32 v4, 0x3400
	global_atomic_add v4, v5, s[22:23]
	v_readfirstlane_b32 s27, v3
	s_add_u32 s34, s26, 1
	s_mul_i32 s27, s34, s27
	s_mov_b32 s35, 0

.LBB0_1226:
	s_mov_b64 s[0:1], s[88:89]
	s_getreg_b32 s8, hwreg(HW_REG_XCC_ID, 0, 4)
	s_waitcnt vmcnt(0)
	s_waitcnt lgkmcnt(0)
	s_barrier
	s_mov_b64 s[10:11], exec
	v_readlane_b32 s22, v254, 5
	v_readlane_b32 s23, v254, 6
	s_and_b64 s[22:23], s[10:11], s[22:23]
	s_mov_b64 exec, s[22:23]
	s_cbranch_execz .LBB0_1162
	buffer_inv sc1
	s_load_dwordx2 s[22:23], s[0:1], 0x170
	v_readlane_b32 s24, v254, 45
	v_readlane_b32 s25, v254, 46
	s_and_b32 s8, s8, 15
	v_mov_b32_e32 v0, s24
	v_mov_b32_e32 v1, s25
	ds_read_b32 v2, v0
	ds_read_b32 v3, v1
	s_lshl_b32 s9, s8, 8
	v_mov_b32_e32 v4, 0x1400
	v_mov_b32_e32 v5, 1
	s_waitcnt lgkmcnt(0)
	s_add_u32 s24, s22, s9
	s_addc_u32 s25, s23, 0
	global_atomic_add v6, v4, v5, s[24:25] sc0
	v_cvt_f32_u32_e32 v7, v2
	v_rcp_f32_e32 v7, v7
	s_waitcnt vmcnt(0)
	v_cvt_f32_u32_e32 v8, v6
	v_add_f32_e32 v8, 0.5, v8
	v_mul_f32_e32 v8, v8, v7
	v_cvt_u32_f32_e32 v8, v8
	v_mul_lo_u32 v9, v8, v2
	v_sub_u32_e32 v9, v6, v9
	v_add_u32_e32 v9, 1, v9
	v_cmp_eq_u32_e32 vcc, v9, v2
	v_readfirstlane_b32 s26, v8
	s_cbranch_vccz .Lhb4_follow
	buffer_wbl2 sc1
	s_waitcnt vmcnt(0)
	v_mov_b32_e32 v4, 0x3400
	global_atomic_add v4, v5, s[22:23]
	v_readfirstlane_b32 s27, v3
	s_add_u32 s34, s26, 1
	s_mul_i32 s27, s34, s27
	s_mov_b32 s35, 0

.Lhb4_fspin:
	global_load_dword v10, v4, s[24:25] sc1
	s_waitcnt vmcnt(0)
	v_readfirstlane_b32 s36, v10
	s_cmp_lg_u32 s36, s26
	s_cbranch_scc1 .LBB0_1162
	s_sleep 1
	s_add_u32 s35, s35, 1
	s_cmp_lt_u32 s35, 0x400000
	s_cbranch_scc1 .Lhb4_fspin
	s_branch .LBB0_1162
	buffer_inv sc1
	s_load_dwordx2 s[22:23], s[0:1], 0x170
	v_readlane_b32 s0, v254, 45
	s_waitcnt expcnt(0) lgkmcnt(0)
	s_and_b32 s42, s8, 15
	v_mov_b32_e32 v0, s0
	ds_read_b32 v2, v0
	v_readlane_b32 s0, v254, 46
	s_waitcnt lgkmcnt(0)
	v_cmp_ne_u32_e32 vcc, 0, v2
	v_mov_b32_e32 v0, s0
	ds_read_b32 v0, v0
	s_cbranch_vccnz .LBB0_1242
	s_add_u32 s24, s22, 0x1000
	s_addc_u32 s25, s23, 0
	s_add_u32 s26, s22, 0x1100
	s_addc_u32 s27, s23, 0
	s_add_u32 s34, s22, 0x1200
	s_addc_u32 s35, s23, 0
	s_add_u32 s36, s22, 0x1300
	s_addc_u32 s37, s23, 0
	s_mov_b32 s8, 1
	s_branch .LBB0_1230

.Lhb5_exit:
	s_getpc_b64 s[98:99]

.LBB0_1292:
	buffer_inv sc1
	s_load_dwordx2 s[22:23], s[0:1], 0x170
	v_readlane_b32 s24, v254, 45
	v_readlane_b32 s25, v254, 46
	s_and_b32 s8, s8, 15
	v_mov_b32_e32 v0, s24
	v_mov_b32_e32 v1, s25
	ds_read_b32 v2, v0
	ds_read_b32 v3, v1
	s_lshl_b32 s9, s8, 8
	v_mov_b32_e32 v4, 0x1400
	v_mov_b32_e32 v5, 1
	s_waitcnt lgkmcnt(0)
	s_add_u32 s24, s22, s9
	s_addc_u32 s25, s23, 0
	global_atomic_add v6, v4, v5, s[24:25] sc0
	v_cvt_f32_u32_e32 v7, v2
	v_rcp_f32_e32 v7, v7
	s_waitcnt vmcnt(0)
	v_cvt_f32_u32_e32 v8, v6
	v_add_f32_e32 v8, 0.5, v8
	v_mul_f32_e32 v8, v8, v7
	v_cvt_u32_f32_e32 v8, v8
	v_mul_lo_u32 v9, v8, v2
	v_sub_u32_e32 v9, v6, v9
	v_add_u32_e32 v9, 1, v9
	v_cmp_eq_u32_e32 vcc, v9, v2
	v_readfirstlane_b32 s26, v8
	s_cbranch_vccz .Lhb5_follow
	buffer_wbl2 sc1
	s_waitcnt vmcnt(0)
	v_mov_b32_e32 v4, 0x3400
	global_atomic_add v4, v5, s[22:23]
	v_readfirstlane_b32 s27, v3
	s_add_u32 s34, s26, 1
	s_mul_i32 s27, s34, s27
	s_mov_b32 s35, 0
